# P3 fused epilogue: batched double-buffered base loads, gains loaded once, no store-ack waits; stats slot loads batched
# speedup vs baseline: 1.0105x; 1.0105x over previous
.LBB0_1123:
	s_waitcnt vmcnt(0) lgkmcnt(0)
	s_barrier
	s_lshl_b32 s27, s24, 8
	v_add_u32_e32 v132, s27, v155
	v_ashrrev_i32_e32 v133, 31, v132
	s_and_saveexec_b64 s[30:31], s[4:5]
	s_cbranch_execz .LBB0_1125
	v_lshlrev_b64 v[0:1], 5, v[132:133]
	v_lshl_add_u64 v[0:1], s[8:9], 0, v[0:1]
	global_load_dwordx2 v[134:135], v[0:1], off sc1
	global_load_dwordx2 v[196:197], v[0:1], off offset:8 sc1
	global_load_dwordx2 v[200:201], v[0:1], off offset:16 sc1
	global_load_dwordx2 v[0:1], v[0:1], off offset:24 sc1
	s_mov_b32 s8, 0xf800000
	s_waitcnt vmcnt(0) lgkmcnt(0)
	v_add_f32_e32 v2, 0, v134
	v_add_f32_e32 v2, v2, v196
	v_add_f32_e32 v2, v2, v200
	v_add_f32_e32 v0, v2, v0
	v_fmamk_f32 v0, v0, 0x3a800000, v158
	v_cmp_gt_f32_e32 vcc, s8, v0
	v_mul_f32_e32 v1, 0x4f800000, v0
	s_nop 0
	v_cndmask_b32_e32 v0, v0, v1, vcc
	v_sqrt_f32_e32 v1, v0
	s_nop 0
	v_add_u32_e32 v2, -1, v1
	v_fma_f32 v134, -v2, v1, v0
	v_cmp_ge_f32_e64 s[8:9], 0, v134
	v_add_u32_e32 v134, 1, v1
	s_nop 0
	v_cndmask_b32_e64 v2, v1, v2, s[8:9]
	v_fma_f32 v1, -v134, v1, v0
	v_cmp_lt_f32_e64 s[8:9], 0, v1
	s_nop 1
	v_cndmask_b32_e64 v1, v2, v134, s[8:9]
	v_mul_f32_e32 v2, 0x37800000, v1
	v_cndmask_b32_e32 v1, v1, v2, vcc
	v_cmp_class_f32_e32 vcc, v0, v232
	s_nop 1
	v_cndmask_b32_e32 v0, v1, v0, vcc
	v_div_scale_f32 v1, s[8:9], v0, v0, 1.0
	v_rcp_f32_e32 v2, v1
	s_nop 0
	v_fma_f32 v134, -v1, v2, 1.0
	v_fmac_f32_e32 v2, v134, v2
	v_div_scale_f32 v134, vcc, 1.0, v0, 1.0
	v_mul_f32_e32 v135, v134, v2
	v_fma_f32 v136, -v1, v135, v134
	v_fmac_f32_e32 v135, v136, v2
	v_fma_f32 v1, -v1, v135, v134
	v_div_fmas_f32 v1, v1, v2, v135
	v_div_fixup_f32 v0, v1, v0, 1.0
	v_lshl_add_u32 v1, v155, 2, 0
	ds_write_b32 v1, v0 offset:8192
.LBB0_1125:
	s_or_b64 exec, exec, s[30:31]
	s_and_b64 s[8:9], s[80:81], exec
	s_cselect_b32 s9, s13, s19
	s_cselect_b32 s8, s12, s18
	s_lshl_b64 s[12:13], s[90:91], 12
	s_add_u32 s12, s16, s12
	s_addc_u32 s13, s17, s13
	s_lshl_b32 s16, s25, 5
	s_lshl_b32 s17, s26, 8
	s_or_b32 s16, s17, s16
	v_lshrrev_b32_e32 v0, 2, v140
	v_add_u32_e32 v134, s27, v141
	v_and_or_b32 v0, v0, 12, s16
	v_ashrrev_i32_e32 v135, 31, v134
	v_ashrrev_i32_e32 v1, 31, v0
	v_lshlrev_b64 v[136:137], 10, v[134:135]
	s_waitcnt lgkmcnt(0)
	v_lshl_add_u32 v2, v141, 2, 0
	v_lshl_add_u64 v[140:141], v[136:137], 0, v[0:1]
	v_lshlrev_b64 v[146:147], 2, v[140:141]
	s_waitcnt lgkmcnt(0)
	s_barrier
	v_lshlrev_b32_e32 v144, 2, v0
	global_load_dwordx4 v[224:227], v144, s[12:13]
	global_load_dwordx2 v[196:197], v144, s[12:13] offset:64
	global_load_dwordx2 v[200:201], v144, s[12:13] offset:72
	global_load_dwordx2 v[228:229], v144, s[12:13] offset:512
	global_load_dwordx2 v[250:251], v144, s[12:13] offset:520
	global_load_dwordx2 v[254:255], v144, s[12:13] offset:576
	global_load_dwordx2 v[180:181], v144, s[12:13] offset:584
	global_load_dwordx4 v[136:139], v146, s[8:9]
	global_load_dwordx4 v[140:143], v146, s[8:9] offset:64
	global_load_dwordx4 v[148:151], v146, s[8:9] offset:512
	global_load_dwordx4 v[168:171], v146, s[8:9] offset:576
	v_add_u32_e32 v198, 0x10000, v146
	global_load_dwordx4 v[172:175], v198, s[8:9]
	global_load_dwordx4 v[176:179], v198, s[8:9] offset:64
	global_load_dwordx4 v[242:245], v198, s[8:9] offset:512
	global_load_dwordx4 v[246:249], v198, s[8:9] offset:576
	ds_read_b32 v190, v2 offset:8192
	ds_read_b32 v192, v2 offset:8256
	s_waitcnt lgkmcnt(1)
	v_pk_mul_f32 v[100:101], v[100:101], v[190:191] op_sel_hi:[1,0]
	v_pk_mul_f32 v[102:103], v[102:103], v[190:191] op_sel_hi:[1,0]
	v_pk_mul_f32 v[120:121], v[120:121], v[190:191] op_sel_hi:[1,0]
	v_pk_mul_f32 v[122:123], v[122:123], v[190:191] op_sel_hi:[1,0]
	v_pk_mul_f32 v[116:117], v[116:117], v[190:191] op_sel_hi:[1,0]
	v_pk_mul_f32 v[118:119], v[118:119], v[190:191] op_sel_hi:[1,0]
	v_pk_mul_f32 v[108:109], v[108:109], v[190:191] op_sel_hi:[1,0]
	v_pk_mul_f32 v[110:111], v[110:111], v[190:191] op_sel_hi:[1,0]
	s_waitcnt vmcnt(4)
	v_pk_fma_f32 v[100:101], v[224:225], v[100:101], v[136:137]
	v_pk_fma_f32 v[102:103], v[226:227], v[102:103], v[138:139]
	v_pk_fma_f32 v[120:121], v[196:197], v[120:121], v[140:141]
	v_pk_fma_f32 v[122:123], v[200:201], v[122:123], v[142:143]
	v_pk_fma_f32 v[116:117], v[228:229], v[116:117], v[148:149]
	v_pk_fma_f32 v[118:119], v[250:251], v[118:119], v[150:151]
	v_pk_fma_f32 v[108:109], v[254:255], v[108:109], v[168:169]
	v_pk_fma_f32 v[110:111], v[180:181], v[110:111], v[170:171]
	global_store_dwordx4 v146, v[100:103], s[18:19]
	global_store_dwordx4 v146, v[120:123], s[18:19] offset:64
	global_store_dwordx4 v146, v[116:119], s[18:19] offset:512
	global_store_dwordx4 v146, v[108:111], s[18:19] offset:576
	v_add_u32_e32 v198, 0x20000, v146
	global_load_dwordx4 v[136:139], v198, s[8:9]
	global_load_dwordx4 v[140:143], v198, s[8:9] offset:64
	global_load_dwordx4 v[148:151], v198, s[8:9] offset:512
	global_load_dwordx4 v[168:171], v198, s[8:9] offset:576
	ds_read_b32 v190, v2 offset:8320
	s_waitcnt lgkmcnt(1)
	v_pk_mul_f32 v[128:129], v[128:129], v[192:193] op_sel_hi:[1,0]
	v_pk_mul_f32 v[130:131], v[130:131], v[192:193] op_sel_hi:[1,0]
	v_pk_mul_f32 v[124:125], v[124:125], v[192:193] op_sel_hi:[1,0]
	v_pk_mul_f32 v[126:127], v[126:127], v[192:193] op_sel_hi:[1,0]
	v_pk_mul_f32 v[112:113], v[112:113], v[192:193] op_sel_hi:[1,0]
	v_pk_mul_f32 v[114:115], v[114:115], v[192:193] op_sel_hi:[1,0]
	v_pk_mul_f32 v[104:105], v[104:105], v[192:193] op_sel_hi:[1,0]
	v_pk_mul_f32 v[106:107], v[106:107], v[192:193] op_sel_hi:[1,0]
	s_waitcnt vmcnt(8)
	v_pk_fma_f32 v[128:129], v[224:225], v[128:129], v[172:173]
	v_pk_fma_f32 v[130:131], v[226:227], v[130:131], v[174:175]
	v_pk_fma_f32 v[124:125], v[196:197], v[124:125], v[176:177]
	v_pk_fma_f32 v[126:127], v[200:201], v[126:127], v[178:179]
	v_pk_fma_f32 v[112:113], v[228:229], v[112:113], v[242:243]
	v_pk_fma_f32 v[114:115], v[250:251], v[114:115], v[244:245]
	v_pk_fma_f32 v[104:105], v[254:255], v[104:105], v[246:247]
	v_pk_fma_f32 v[106:107], v[180:181], v[106:107], v[248:249]
	v_add_u32_e32 v145, 0x10000, v146
	global_store_dwordx4 v145, v[128:131], s[18:19]
	global_store_dwordx4 v145, v[124:127], s[18:19] offset:64
	global_store_dwordx4 v145, v[112:115], s[18:19] offset:512
	global_store_dwordx4 v145, v[104:107], s[18:19] offset:576
	v_add_u32_e32 v198, 0x30000, v146
	global_load_dwordx4 v[172:175], v198, s[8:9]
	global_load_dwordx4 v[176:179], v198, s[8:9] offset:64
	global_load_dwordx4 v[242:245], v198, s[8:9] offset:512
	global_load_dwordx4 v[246:249], v198, s[8:9] offset:576
	ds_read_b32 v192, v2 offset:8384
	s_waitcnt lgkmcnt(1)
	v_pk_mul_f32 v[96:97], v[96:97], v[190:191] op_sel_hi:[1,0]
	v_pk_mul_f32 v[98:99], v[98:99], v[190:191] op_sel_hi:[1,0]
	v_pk_mul_f32 v[92:93], v[92:93], v[190:191] op_sel_hi:[1,0]
	v_pk_mul_f32 v[94:95], v[94:95], v[190:191] op_sel_hi:[1,0]
	v_pk_mul_f32 v[88:89], v[88:89], v[190:191] op_sel_hi:[1,0]
	v_pk_mul_f32 v[90:91], v[90:91], v[190:191] op_sel_hi:[1,0]
	v_pk_mul_f32 v[84:85], v[84:85], v[190:191] op_sel_hi:[1,0]
	v_pk_mul_f32 v[86:87], v[86:87], v[190:191] op_sel_hi:[1,0]
	s_waitcnt vmcnt(8)
	v_pk_fma_f32 v[96:97], v[224:225], v[96:97], v[136:137]
	v_pk_fma_f32 v[98:99], v[226:227], v[98:99], v[138:139]
	v_pk_fma_f32 v[92:93], v[196:197], v[92:93], v[140:141]
	v_pk_fma_f32 v[94:95], v[200:201], v[94:95], v[142:143]
	v_pk_fma_f32 v[88:89], v[228:229], v[88:89], v[148:149]
	v_pk_fma_f32 v[90:91], v[250:251], v[90:91], v[150:151]
	v_pk_fma_f32 v[84:85], v[254:255], v[84:85], v[168:169]
	v_pk_fma_f32 v[86:87], v[180:181], v[86:87], v[170:171]
	v_add_u32_e32 v145, 0x20000, v146
	global_store_dwordx4 v145, v[96:99], s[18:19]
	global_store_dwordx4 v145, v[92:95], s[18:19] offset:64
	global_store_dwordx4 v145, v[88:91], s[18:19] offset:512
	global_store_dwordx4 v145, v[84:87], s[18:19] offset:576
	v_add_u32_e32 v198, 0x80000, v146
	global_load_dwordx4 v[136:139], v198, s[8:9]
	global_load_dwordx4 v[140:143], v198, s[8:9] offset:64
	global_load_dwordx4 v[148:151], v198, s[8:9] offset:512
	global_load_dwordx4 v[168:171], v198, s[8:9] offset:576
	ds_read_b32 v190, v2 offset:8704
	s_waitcnt lgkmcnt(1)
	v_pk_mul_f32 v[80:81], v[80:81], v[192:193] op_sel_hi:[1,0]
	v_pk_mul_f32 v[82:83], v[82:83], v[192:193] op_sel_hi:[1,0]
	v_pk_mul_f32 v[76:77], v[76:77], v[192:193] op_sel_hi:[1,0]
	v_pk_mul_f32 v[78:79], v[78:79], v[192:193] op_sel_hi:[1,0]
	v_pk_mul_f32 v[72:73], v[72:73], v[192:193] op_sel_hi:[1,0]
	v_pk_mul_f32 v[74:75], v[74:75], v[192:193] op_sel_hi:[1,0]
	v_pk_mul_f32 v[68:69], v[68:69], v[192:193] op_sel_hi:[1,0]
	v_pk_mul_f32 v[70:71], v[70:71], v[192:193] op_sel_hi:[1,0]
	s_waitcnt vmcnt(8)
	v_pk_fma_f32 v[80:81], v[224:225], v[80:81], v[172:173]
	v_pk_fma_f32 v[82:83], v[226:227], v[82:83], v[174:175]
	v_pk_fma_f32 v[76:77], v[196:197], v[76:77], v[176:177]
	v_pk_fma_f32 v[78:79], v[200:201], v[78:79], v[178:179]
	v_pk_fma_f32 v[72:73], v[228:229], v[72:73], v[242:243]
	v_pk_fma_f32 v[74:75], v[250:251], v[74:75], v[244:245]
	v_pk_fma_f32 v[68:69], v[254:255], v[68:69], v[246:247]
	v_pk_fma_f32 v[70:71], v[180:181], v[70:71], v[248:249]
	v_add_u32_e32 v145, 0x30000, v146
	global_store_dwordx4 v145, v[80:83], s[18:19]
	global_store_dwordx4 v145, v[76:79], s[18:19] offset:64
	global_store_dwordx4 v145, v[72:75], s[18:19] offset:512
	global_store_dwordx4 v145, v[68:71], s[18:19] offset:576
	v_add_u32_e32 v198, 0x90000, v146
	global_load_dwordx4 v[172:175], v198, s[8:9]
	global_load_dwordx4 v[176:179], v198, s[8:9] offset:64
	global_load_dwordx4 v[242:245], v198, s[8:9] offset:512
	global_load_dwordx4 v[246:249], v198, s[8:9] offset:576
	ds_read_b32 v192, v2 offset:8768
	s_waitcnt lgkmcnt(1)
	v_pk_mul_f32 v[64:65], v[64:65], v[190:191] op_sel_hi:[1,0]
	v_pk_mul_f32 v[66:67], v[66:67], v[190:191] op_sel_hi:[1,0]
	v_pk_mul_f32 v[60:61], v[60:61], v[190:191] op_sel_hi:[1,0]
	v_pk_mul_f32 v[62:63], v[62:63], v[190:191] op_sel_hi:[1,0]
	v_pk_mul_f32 v[56:57], v[56:57], v[190:191] op_sel_hi:[1,0]
	v_pk_mul_f32 v[58:59], v[58:59], v[190:191] op_sel_hi:[1,0]
	v_pk_mul_f32 v[52:53], v[52:53], v[190:191] op_sel_hi:[1,0]
	v_pk_mul_f32 v[54:55], v[54:55], v[190:191] op_sel_hi:[1,0]
	s_waitcnt vmcnt(8)
	v_pk_fma_f32 v[64:65], v[224:225], v[64:65], v[136:137]
	v_pk_fma_f32 v[66:67], v[226:227], v[66:67], v[138:139]
	v_pk_fma_f32 v[60:61], v[196:197], v[60:61], v[140:141]
	v_pk_fma_f32 v[62:63], v[200:201], v[62:63], v[142:143]
	v_pk_fma_f32 v[56:57], v[228:229], v[56:57], v[148:149]
	v_pk_fma_f32 v[58:59], v[250:251], v[58:59], v[150:151]
	v_pk_fma_f32 v[52:53], v[254:255], v[52:53], v[168:169]
	v_pk_fma_f32 v[54:55], v[180:181], v[54:55], v[170:171]
	v_add_u32_e32 v145, 0x80000, v146
	global_store_dwordx4 v145, v[64:67], s[18:19]
	global_store_dwordx4 v145, v[60:63], s[18:19] offset:64
	global_store_dwordx4 v145, v[56:59], s[18:19] offset:512
	global_store_dwordx4 v145, v[52:55], s[18:19] offset:576
	v_add_u32_e32 v198, 0xa0000, v146
	global_load_dwordx4 v[136:139], v198, s[8:9]
	global_load_dwordx4 v[140:143], v198, s[8:9] offset:64
	global_load_dwordx4 v[148:151], v198, s[8:9] offset:512
	global_load_dwordx4 v[168:171], v198, s[8:9] offset:576
	ds_read_b32 v190, v2 offset:8832
	s_waitcnt lgkmcnt(1)
	v_pk_mul_f32 v[48:49], v[48:49], v[192:193] op_sel_hi:[1,0]
	v_pk_mul_f32 v[50:51], v[50:51], v[192:193] op_sel_hi:[1,0]
	v_pk_mul_f32 v[44:45], v[44:45], v[192:193] op_sel_hi:[1,0]
	v_pk_mul_f32 v[46:47], v[46:47], v[192:193] op_sel_hi:[1,0]
	v_pk_mul_f32 v[40:41], v[40:41], v[192:193] op_sel_hi:[1,0]
	v_pk_mul_f32 v[42:43], v[42:43], v[192:193] op_sel_hi:[1,0]
	v_pk_mul_f32 v[36:37], v[36:37], v[192:193] op_sel_hi:[1,0]
	v_pk_mul_f32 v[38:39], v[38:39], v[192:193] op_sel_hi:[1,0]
	s_waitcnt vmcnt(8)
	v_pk_fma_f32 v[48:49], v[224:225], v[48:49], v[172:173]
	v_pk_fma_f32 v[50:51], v[226:227], v[50:51], v[174:175]
	v_pk_fma_f32 v[44:45], v[196:197], v[44:45], v[176:177]
	v_pk_fma_f32 v[46:47], v[200:201], v[46:47], v[178:179]
	v_pk_fma_f32 v[40:41], v[228:229], v[40:41], v[242:243]
	v_pk_fma_f32 v[42:43], v[250:251], v[42:43], v[244:245]
	v_pk_fma_f32 v[36:37], v[254:255], v[36:37], v[246:247]
	v_pk_fma_f32 v[38:39], v[180:181], v[38:39], v[248:249]
	v_add_u32_e32 v145, 0x90000, v146
	global_store_dwordx4 v145, v[48:51], s[18:19]
	global_store_dwordx4 v145, v[44:47], s[18:19] offset:64
	global_store_dwordx4 v145, v[40:43], s[18:19] offset:512
	global_store_dwordx4 v145, v[36:39], s[18:19] offset:576
	v_add_u32_e32 v198, 0xb0000, v146
	global_load_dwordx4 v[172:175], v198, s[8:9]
	global_load_dwordx4 v[176:179], v198, s[8:9] offset:64
	global_load_dwordx4 v[242:245], v198, s[8:9] offset:512
	global_load_dwordx4 v[246:249], v198, s[8:9] offset:576
	ds_read_b32 v192, v2 offset:8896
	s_waitcnt lgkmcnt(1)
	v_pk_mul_f32 v[32:33], v[32:33], v[190:191] op_sel_hi:[1,0]
	v_pk_mul_f32 v[34:35], v[34:35], v[190:191] op_sel_hi:[1,0]
	v_pk_mul_f32 v[28:29], v[28:29], v[190:191] op_sel_hi:[1,0]
	v_pk_mul_f32 v[30:31], v[30:31], v[190:191] op_sel_hi:[1,0]
	v_pk_mul_f32 v[24:25], v[24:25], v[190:191] op_sel_hi:[1,0]
	v_pk_mul_f32 v[26:27], v[26:27], v[190:191] op_sel_hi:[1,0]
	v_pk_mul_f32 v[20:21], v[20:21], v[190:191] op_sel_hi:[1,0]
	v_pk_mul_f32 v[22:23], v[22:23], v[190:191] op_sel_hi:[1,0]
	s_waitcnt vmcnt(8)
	v_pk_fma_f32 v[32:33], v[224:225], v[32:33], v[136:137]
	v_pk_fma_f32 v[34:35], v[226:227], v[34:35], v[138:139]
	v_pk_fma_f32 v[28:29], v[196:197], v[28:29], v[140:141]
	v_pk_fma_f32 v[30:31], v[200:201], v[30:31], v[142:143]
	v_pk_fma_f32 v[24:25], v[228:229], v[24:25], v[148:149]
	v_pk_fma_f32 v[26:27], v[250:251], v[26:27], v[150:151]
	v_pk_fma_f32 v[20:21], v[254:255], v[20:21], v[168:169]
	v_pk_fma_f32 v[22:23], v[180:181], v[22:23], v[170:171]
	v_add_u32_e32 v145, 0xa0000, v146
	global_store_dwordx4 v145, v[32:35], s[18:19]
	global_store_dwordx4 v145, v[28:31], s[18:19] offset:64
	global_store_dwordx4 v145, v[24:27], s[18:19] offset:512
	global_store_dwordx4 v145, v[20:23], s[18:19] offset:576
	s_waitcnt lgkmcnt(0)
	v_pk_mul_f32 v[16:17], v[16:17], v[192:193] op_sel_hi:[1,0]
	v_pk_mul_f32 v[18:19], v[18:19], v[192:193] op_sel_hi:[1,0]
	v_pk_mul_f32 v[12:13], v[12:13], v[192:193] op_sel_hi:[1,0]
	v_pk_mul_f32 v[14:15], v[14:15], v[192:193] op_sel_hi:[1,0]
	v_pk_mul_f32 v[8:9], v[8:9], v[192:193] op_sel_hi:[1,0]
	v_pk_mul_f32 v[10:11], v[10:11], v[192:193] op_sel_hi:[1,0]
	v_pk_mul_f32 v[4:5], v[4:5], v[192:193] op_sel_hi:[1,0]
	v_pk_mul_f32 v[6:7], v[6:7], v[192:193] op_sel_hi:[1,0]
	s_waitcnt vmcnt(4)
	v_pk_fma_f32 v[16:17], v[224:225], v[16:17], v[172:173]
	v_pk_fma_f32 v[18:19], v[226:227], v[18:19], v[174:175]
	v_pk_fma_f32 v[12:13], v[196:197], v[12:13], v[176:177]
	v_pk_fma_f32 v[14:15], v[200:201], v[14:15], v[178:179]
	v_pk_fma_f32 v[8:9], v[228:229], v[8:9], v[242:243]
	v_pk_fma_f32 v[10:11], v[250:251], v[10:11], v[244:245]
	v_pk_fma_f32 v[4:5], v[254:255], v[4:5], v[246:247]
	v_pk_fma_f32 v[6:7], v[180:181], v[6:7], v[248:249]
	v_add_u32_e32 v145, 0xb0000, v146
	global_store_dwordx4 v145, v[16:19], s[18:19]
	global_store_dwordx4 v145, v[12:15], s[18:19] offset:64
	global_store_dwordx4 v145, v[8:11], s[18:19] offset:512
	global_store_dwordx4 v145, v[4:7], s[18:19] offset:576
	s_mov_b64 s[8:9], 0
	s_andn2_b64 vcc, exec, s[80:81]
	s_nop 1
	s_cbranch_vccnz .LBB0_1162
	v_mul_f32_e32 v150, v101, v101
	v_mul_f32_e32 v151, v103, v103
	v_fmac_f32_e32 v150, v100, v100
	v_fmac_f32_e32 v151, v102, v102
	v_add_f32_e32 v150, v150, v151
	v_mul_f32_e32 v151, v121, v121
	v_mul_f32_e32 v161, v123, v123
	v_fmac_f32_e32 v151, v120, v120
	v_fmac_f32_e32 v161, v122, v122
	v_add_f32_e32 v151, v151, v161
	v_add_f32_e32 v150, v150, v151
	v_mul_f32_e32 v151, v117, v117
	v_mul_f32_e32 v161, v119, v119
	v_fmac_f32_e32 v151, v116, v116
	v_fmac_f32_e32 v161, v118, v118
	v_add_f32_e32 v151, v151, v161
	v_add_f32_e32 v150, v151, v150
	v_mul_f32_e32 v151, v109, v109
	v_mul_f32_e32 v161, v111, v111
	v_fmac_f32_e32 v151, v108, v108
	v_fmac_f32_e32 v161, v110, v110
	v_add_f32_e32 v151, v151, v161
	v_add_f32_e32 v150, v151, v150
	ds_bpermute_b32 v151, v153, v150
	s_waitcnt lgkmcnt(0)
	v_add_f32_e32 v150, v150, v151
	ds_bpermute_b32 v151, v154, v150
	s_and_saveexec_b64 s[8:9], s[2:3]
	s_cbranch_execz .LBB0_1128
	s_lshl_b32 s12, s0, 10
	s_add_i32 s12, s1, s12
	v_lshl_add_u32 v161, v152, 4, s12
	s_waitcnt lgkmcnt(0)
	v_add_f32_e32 v150, v150, v151
	ds_write_b32 v161, v150

.LBB0_1159:
	s_waitcnt vmcnt(0) lgkmcnt(0)
	s_barrier
	s_and_saveexec_b64 s[6:7], s[4:5]
	s_cbranch_execz .LBB0_1161
	v_lshlrev_b64 v[132:133], 5, v[132:133]
	v_lshl_add_u64 v[132:133], s[2:3], 0, v[132:133]
	s_waitcnt lgkmcnt(0)
	global_load_dwordx2 v[150:151], v[132:133], off sc1
	global_load_dwordx2 v[196:197], v[132:133], off offset:8 sc1
	global_load_dwordx2 v[200:201], v[132:133], off offset:16 sc1
	global_load_dwordx2 v[132:133], v[132:133], off offset:24 sc1
	s_mov_b32 s0, 0xf800000
	s_waitcnt vmcnt(0)
	v_add_f32_e32 v152, 0, v150
	v_add_f32_e32 v152, v152, v196
	v_add_f32_e32 v150, v152, v200
	v_add_f32_e32 v132, v150, v132
	v_fmamk_f32 v132, v132, 0x3a800000, v158
	v_cmp_gt_f32_e32 vcc, s0, v132
	v_mul_f32_e32 v133, 0x4f800000, v132
	s_nop 0
	v_cndmask_b32_e32 v132, v132, v133, vcc
	v_sqrt_f32_e32 v133, v132
	s_nop 0
	v_add_u32_e32 v150, -1, v133
	v_fma_f32 v151, -v150, v133, v132
	v_cmp_ge_f32_e64 s[2:3], 0, v151
	v_add_u32_e32 v151, 1, v133
	s_nop 0
	v_cndmask_b32_e64 v150, v133, v150, s[2:3]
	v_fma_f32 v133, -v151, v133, v132
	v_cmp_lt_f32_e64 s[2:3], 0, v133
	s_nop 1
	v_cndmask_b32_e64 v133, v150, v151, s[2:3]
	v_mul_f32_e32 v150, 0x37800000, v133
	v_cndmask_b32_e32 v133, v133, v150, vcc
	v_cmp_class_f32_e32 vcc, v132, v232
	s_nop 1
	v_cndmask_b32_e32 v132, v133, v132, vcc
	v_div_scale_f32 v133, s[0:1], v132, v132, 1.0
	v_rcp_f32_e32 v150, v133
	s_nop 0
	v_fma_f32 v151, -v133, v150, 1.0
	v_fmac_f32_e32 v150, v151, v150
	v_div_scale_f32 v151, vcc, 1.0, v132, 1.0
	v_mul_f32_e32 v152, v151, v150
	v_fma_f32 v153, -v133, v152, v151
	v_fmac_f32_e32 v152, v153, v150
	v_fma_f32 v133, -v133, v152, v151
	v_div_fmas_f32 v133, v133, v150, v152
	v_div_fixup_f32 v132, v133, v132, 1.0
	v_lshl_add_u32 v133, v155, 2, 0
	ds_write_b32 v133, v132 offset:8192
.LBB0_1161:
	s_or_b64 exec, exec, s[6:7]
	s_add_u32 s2, s14, 0x1000
	s_addc_u32 s3, s15, 0
	s_and_b64 s[0:1], s[80:81], exec
	s_cselect_b32 s0, s3, 0
	s_cselect_b32 s1, s2, 0
	v_mov_b32_e32 v132, s1
	v_mov_b32_e32 v133, s0
	s_waitcnt lgkmcnt(0)
	s_barrier
	v_lshl_add_u64 v[132:133], v[0:1], 2, v[132:133]
	s_waitcnt lgkmcnt(0)
	global_load_dwordx4 v[224:227], v[132:133], off
	global_load_dwordx4 v[242:245], v[132:133], off offset:64
	global_load_dwordx4 v[246:249], v[132:133], off offset:512
	global_load_dwordx4 v[136:139], v[132:133], off offset:576
	ds_read_b32 v190, v2 offset:8192
	ds_read_b32 v192, v2 offset:8256
	v_lshlrev_b32_e32 v144, 11, v134
	v_lshl_add_u32 v144, v0, 1, v144
	s_mov_b64 s[8:9], -1
	s_waitcnt lgkmcnt(1)
	v_pk_mul_f32 v[100:101], v[100:101], v[190:191] op_sel_hi:[1,0]
	v_pk_mul_f32 v[102:103], v[102:103], v[190:191] op_sel_hi:[1,0]
	v_pk_mul_f32 v[120:121], v[120:121], v[190:191] op_sel_hi:[1,0]
	v_pk_mul_f32 v[122:123], v[122:123], v[190:191] op_sel_hi:[1,0]
	v_pk_mul_f32 v[116:117], v[116:117], v[190:191] op_sel_hi:[1,0]
	v_pk_mul_f32 v[118:119], v[118:119], v[190:191] op_sel_hi:[1,0]
	v_pk_mul_f32 v[108:109], v[108:109], v[190:191] op_sel_hi:[1,0]
	v_pk_mul_f32 v[110:111], v[110:111], v[190:191] op_sel_hi:[1,0]
	s_waitcnt vmcnt(0)
	v_pk_mul_f32 v[100:101], v[224:225], v[100:101]
	v_pk_mul_f32 v[102:103], v[226:227], v[102:103]
	v_pk_mul_f32 v[120:121], v[242:243], v[120:121]
	v_pk_mul_f32 v[122:123], v[244:245], v[122:123]
	v_pk_mul_f32 v[116:117], v[246:247], v[116:117]
	v_pk_mul_f32 v[118:119], v[248:249], v[118:119]
	v_pk_mul_f32 v[108:109], v[136:137], v[108:109]
	v_pk_mul_f32 v[110:111], v[138:139], v[110:111]
	v_cvt_pk_bf16_f32 v100, v100, v101
	v_cvt_pk_bf16_f32 v101, v102, v103
	v_cvt_pk_bf16_f32 v120, v120, v121
	v_cvt_pk_bf16_f32 v121, v122, v123
	v_cvt_pk_bf16_f32 v116, v116, v117
	v_cvt_pk_bf16_f32 v117, v118, v119
	v_cvt_pk_bf16_f32 v108, v108, v109
	v_cvt_pk_bf16_f32 v109, v110, v111
	global_store_dwordx2 v144, v[100:101], s[20:21]
	global_store_dwordx2 v144, v[120:121], s[20:21] offset:32
	global_store_dwordx2 v144, v[116:117], s[20:21] offset:256
	global_store_dwordx2 v144, v[108:109], s[20:21] offset:288
	ds_read_b32 v190, v2 offset:8320
	s_waitcnt lgkmcnt(1)
	v_pk_mul_f32 v[128:129], v[128:129], v[192:193] op_sel_hi:[1,0]
	v_pk_mul_f32 v[130:131], v[130:131], v[192:193] op_sel_hi:[1,0]
	v_pk_mul_f32 v[124:125], v[124:125], v[192:193] op_sel_hi:[1,0]
	v_pk_mul_f32 v[126:127], v[126:127], v[192:193] op_sel_hi:[1,0]
	v_pk_mul_f32 v[112:113], v[112:113], v[192:193] op_sel_hi:[1,0]
	v_pk_mul_f32 v[114:115], v[114:115], v[192:193] op_sel_hi:[1,0]
	v_pk_mul_f32 v[104:105], v[104:105], v[192:193] op_sel_hi:[1,0]
	v_pk_mul_f32 v[106:107], v[106:107], v[192:193] op_sel_hi:[1,0]
	v_pk_mul_f32 v[128:129], v[224:225], v[128:129]
	v_pk_mul_f32 v[130:131], v[226:227], v[130:131]
	v_pk_mul_f32 v[124:125], v[242:243], v[124:125]
	v_pk_mul_f32 v[126:127], v[244:245], v[126:127]
	v_pk_mul_f32 v[112:113], v[246:247], v[112:113]
	v_pk_mul_f32 v[114:115], v[248:249], v[114:115]
	v_pk_mul_f32 v[104:105], v[136:137], v[104:105]
	v_pk_mul_f32 v[106:107], v[138:139], v[106:107]
	v_cvt_pk_bf16_f32 v128, v128, v129
	v_cvt_pk_bf16_f32 v129, v130, v131
	v_cvt_pk_bf16_f32 v124, v124, v125
	v_cvt_pk_bf16_f32 v125, v126, v127
	v_cvt_pk_bf16_f32 v112, v112, v113
	v_cvt_pk_bf16_f32 v113, v114, v115
	v_cvt_pk_bf16_f32 v104, v104, v105
	v_cvt_pk_bf16_f32 v105, v106, v107
	v_add_u32_e32 v145, 0x8000, v144
	global_store_dwordx2 v145, v[128:129], s[20:21]
	global_store_dwordx2 v145, v[124:125], s[20:21] offset:32
	global_store_dwordx2 v145, v[112:113], s[20:21] offset:256
	global_store_dwordx2 v145, v[104:105], s[20:21] offset:288
	ds_read_b32 v192, v2 offset:8384
	s_waitcnt lgkmcnt(1)
	v_pk_mul_f32 v[96:97], v[96:97], v[190:191] op_sel_hi:[1,0]
	v_pk_mul_f32 v[98:99], v[98:99], v[190:191] op_sel_hi:[1,0]
	v_pk_mul_f32 v[92:93], v[92:93], v[190:191] op_sel_hi:[1,0]
	v_pk_mul_f32 v[94:95], v[94:95], v[190:191] op_sel_hi:[1,0]
	v_pk_mul_f32 v[88:89], v[88:89], v[190:191] op_sel_hi:[1,0]
	v_pk_mul_f32 v[90:91], v[90:91], v[190:191] op_sel_hi:[1,0]
	v_pk_mul_f32 v[84:85], v[84:85], v[190:191] op_sel_hi:[1,0]
	v_pk_mul_f32 v[86:87], v[86:87], v[190:191] op_sel_hi:[1,0]
	v_pk_mul_f32 v[96:97], v[224:225], v[96:97]
	v_pk_mul_f32 v[98:99], v[226:227], v[98:99]
	v_pk_mul_f32 v[92:93], v[242:243], v[92:93]
	v_pk_mul_f32 v[94:95], v[244:245], v[94:95]
	v_pk_mul_f32 v[88:89], v[246:247], v[88:89]
	v_pk_mul_f32 v[90:91], v[248:249], v[90:91]
	v_pk_mul_f32 v[84:85], v[136:137], v[84:85]
	v_pk_mul_f32 v[86:87], v[138:139], v[86:87]
	v_cvt_pk_bf16_f32 v96, v96, v97
	v_cvt_pk_bf16_f32 v97, v98, v99
	v_cvt_pk_bf16_f32 v92, v92, v93
	v_cvt_pk_bf16_f32 v93, v94, v95
	v_cvt_pk_bf16_f32 v88, v88, v89
	v_cvt_pk_bf16_f32 v89, v90, v91
	v_cvt_pk_bf16_f32 v84, v84, v85
	v_cvt_pk_bf16_f32 v85, v86, v87
	v_add_u32_e32 v145, 0x10000, v144
	global_store_dwordx2 v145, v[96:97], s[20:21]
	global_store_dwordx2 v145, v[92:93], s[20:21] offset:32
	global_store_dwordx2 v145, v[88:89], s[20:21] offset:256
	global_store_dwordx2 v145, v[84:85], s[20:21] offset:288
	ds_read_b32 v190, v2 offset:8704
	s_waitcnt lgkmcnt(1)
	v_pk_mul_f32 v[80:81], v[80:81], v[192:193] op_sel_hi:[1,0]
	v_pk_mul_f32 v[82:83], v[82:83], v[192:193] op_sel_hi:[1,0]
	v_pk_mul_f32 v[76:77], v[76:77], v[192:193] op_sel_hi:[1,0]
	v_pk_mul_f32 v[78:79], v[78:79], v[192:193] op_sel_hi:[1,0]
	v_pk_mul_f32 v[72:73], v[72:73], v[192:193] op_sel_hi:[1,0]
	v_pk_mul_f32 v[74:75], v[74:75], v[192:193] op_sel_hi:[1,0]
	v_pk_mul_f32 v[68:69], v[68:69], v[192:193] op_sel_hi:[1,0]
	v_pk_mul_f32 v[70:71], v[70:71], v[192:193] op_sel_hi:[1,0]
	v_pk_mul_f32 v[80:81], v[224:225], v[80:81]
	v_pk_mul_f32 v[82:83], v[226:227], v[82:83]
	v_pk_mul_f32 v[76:77], v[242:243], v[76:77]
	v_pk_mul_f32 v[78:79], v[244:245], v[78:79]
	v_pk_mul_f32 v[72:73], v[246:247], v[72:73]
	v_pk_mul_f32 v[74:75], v[248:249], v[74:75]
	v_pk_mul_f32 v[68:69], v[136:137], v[68:69]
	v_pk_mul_f32 v[70:71], v[138:139], v[70:71]
	v_cvt_pk_bf16_f32 v80, v80, v81
	v_cvt_pk_bf16_f32 v81, v82, v83
	v_cvt_pk_bf16_f32 v76, v76, v77
	v_cvt_pk_bf16_f32 v77, v78, v79
	v_cvt_pk_bf16_f32 v72, v72, v73
	v_cvt_pk_bf16_f32 v73, v74, v75
	v_cvt_pk_bf16_f32 v68, v68, v69
	v_cvt_pk_bf16_f32 v69, v70, v71
	v_add_u32_e32 v145, 0x18000, v144
	global_store_dwordx2 v145, v[80:81], s[20:21]
	global_store_dwordx2 v145, v[76:77], s[20:21] offset:32
	global_store_dwordx2 v145, v[72:73], s[20:21] offset:256
	global_store_dwordx2 v145, v[68:69], s[20:21] offset:288
	ds_read_b32 v192, v2 offset:8768
	s_waitcnt lgkmcnt(1)
	v_pk_mul_f32 v[64:65], v[64:65], v[190:191] op_sel_hi:[1,0]
	v_pk_mul_f32 v[66:67], v[66:67], v[190:191] op_sel_hi:[1,0]
	v_pk_mul_f32 v[60:61], v[60:61], v[190:191] op_sel_hi:[1,0]
	v_pk_mul_f32 v[62:63], v[62:63], v[190:191] op_sel_hi:[1,0]
	v_pk_mul_f32 v[56:57], v[56:57], v[190:191] op_sel_hi:[1,0]
	v_pk_mul_f32 v[58:59], v[58:59], v[190:191] op_sel_hi:[1,0]
	v_pk_mul_f32 v[52:53], v[52:53], v[190:191] op_sel_hi:[1,0]
	v_pk_mul_f32 v[54:55], v[54:55], v[190:191] op_sel_hi:[1,0]
	v_pk_mul_f32 v[64:65], v[224:225], v[64:65]
	v_pk_mul_f32 v[66:67], v[226:227], v[66:67]
	v_pk_mul_f32 v[60:61], v[242:243], v[60:61]
	v_pk_mul_f32 v[62:63], v[244:245], v[62:63]
	v_pk_mul_f32 v[56:57], v[246:247], v[56:57]
	v_pk_mul_f32 v[58:59], v[248:249], v[58:59]
	v_pk_mul_f32 v[52:53], v[136:137], v[52:53]
	v_pk_mul_f32 v[54:55], v[138:139], v[54:55]
	v_cvt_pk_bf16_f32 v64, v64, v65
	v_cvt_pk_bf16_f32 v65, v66, v67
	v_cvt_pk_bf16_f32 v60, v60, v61
	v_cvt_pk_bf16_f32 v61, v62, v63
	v_cvt_pk_bf16_f32 v56, v56, v57
	v_cvt_pk_bf16_f32 v57, v58, v59
	v_cvt_pk_bf16_f32 v52, v52, v53
	v_cvt_pk_bf16_f32 v53, v54, v55
	v_add_u32_e32 v145, 0x40000, v144
	global_store_dwordx2 v145, v[64:65], s[20:21]
	global_store_dwordx2 v145, v[60:61], s[20:21] offset:32
	global_store_dwordx2 v145, v[56:57], s[20:21] offset:256
	global_store_dwordx2 v145, v[52:53], s[20:21] offset:288
	ds_read_b32 v190, v2 offset:8832
	s_waitcnt lgkmcnt(1)
	v_pk_mul_f32 v[48:49], v[48:49], v[192:193] op_sel_hi:[1,0]
	v_pk_mul_f32 v[50:51], v[50:51], v[192:193] op_sel_hi:[1,0]
	v_pk_mul_f32 v[44:45], v[44:45], v[192:193] op_sel_hi:[1,0]
	v_pk_mul_f32 v[46:47], v[46:47], v[192:193] op_sel_hi:[1,0]
	v_pk_mul_f32 v[40:41], v[40:41], v[192:193] op_sel_hi:[1,0]
	v_pk_mul_f32 v[42:43], v[42:43], v[192:193] op_sel_hi:[1,0]
	v_pk_mul_f32 v[36:37], v[36:37], v[192:193] op_sel_hi:[1,0]
	v_pk_mul_f32 v[38:39], v[38:39], v[192:193] op_sel_hi:[1,0]
	v_pk_mul_f32 v[48:49], v[224:225], v[48:49]
	v_pk_mul_f32 v[50:51], v[226:227], v[50:51]
	v_pk_mul_f32 v[44:45], v[242:243], v[44:45]
	v_pk_mul_f32 v[46:47], v[244:245], v[46:47]
	v_pk_mul_f32 v[40:41], v[246:247], v[40:41]
	v_pk_mul_f32 v[42:43], v[248:249], v[42:43]
	v_pk_mul_f32 v[36:37], v[136:137], v[36:37]
	v_pk_mul_f32 v[38:39], v[138:139], v[38:39]
	v_cvt_pk_bf16_f32 v48, v48, v49
	v_cvt_pk_bf16_f32 v49, v50, v51
	v_cvt_pk_bf16_f32 v44, v44, v45
	v_cvt_pk_bf16_f32 v45, v46, v47
	v_cvt_pk_bf16_f32 v40, v40, v41
	v_cvt_pk_bf16_f32 v41, v42, v43
	v_cvt_pk_bf16_f32 v36, v36, v37
	v_cvt_pk_bf16_f32 v37, v38, v39
	v_add_u32_e32 v145, 0x48000, v144
	global_store_dwordx2 v145, v[48:49], s[20:21]
	global_store_dwordx2 v145, v[44:45], s[20:21] offset:32
	global_store_dwordx2 v145, v[40:41], s[20:21] offset:256
	global_store_dwordx2 v145, v[36:37], s[20:21] offset:288
	ds_read_b32 v192, v2 offset:8896
	s_waitcnt lgkmcnt(1)
	v_pk_mul_f32 v[32:33], v[32:33], v[190:191] op_sel_hi:[1,0]
	v_pk_mul_f32 v[34:35], v[34:35], v[190:191] op_sel_hi:[1,0]
	v_pk_mul_f32 v[28:29], v[28:29], v[190:191] op_sel_hi:[1,0]
	v_pk_mul_f32 v[30:31], v[30:31], v[190:191] op_sel_hi:[1,0]
	v_pk_mul_f32 v[24:25], v[24:25], v[190:191] op_sel_hi:[1,0]
	v_pk_mul_f32 v[26:27], v[26:27], v[190:191] op_sel_hi:[1,0]
	v_pk_mul_f32 v[20:21], v[20:21], v[190:191] op_sel_hi:[1,0]
	v_pk_mul_f32 v[22:23], v[22:23], v[190:191] op_sel_hi:[1,0]
	v_pk_mul_f32 v[32:33], v[224:225], v[32:33]
	v_pk_mul_f32 v[34:35], v[226:227], v[34:35]
	v_pk_mul_f32 v[28:29], v[242:243], v[28:29]
	v_pk_mul_f32 v[30:31], v[244:245], v[30:31]
	v_pk_mul_f32 v[24:25], v[246:247], v[24:25]
	v_pk_mul_f32 v[26:27], v[248:249], v[26:27]
	v_pk_mul_f32 v[20:21], v[136:137], v[20:21]
	v_pk_mul_f32 v[22:23], v[138:139], v[22:23]
	v_cvt_pk_bf16_f32 v32, v32, v33
	v_cvt_pk_bf16_f32 v33, v34, v35
	v_cvt_pk_bf16_f32 v28, v28, v29
	v_cvt_pk_bf16_f32 v29, v30, v31
	v_cvt_pk_bf16_f32 v24, v24, v25
	v_cvt_pk_bf16_f32 v25, v26, v27
	v_cvt_pk_bf16_f32 v20, v20, v21
	v_cvt_pk_bf16_f32 v21, v22, v23
	v_add_u32_e32 v145, 0x50000, v144
	global_store_dwordx2 v145, v[32:33], s[20:21]
	global_store_dwordx2 v145, v[28:29], s[20:21] offset:32
	global_store_dwordx2 v145, v[24:25], s[20:21] offset:256
	global_store_dwordx2 v145, v[20:21], s[20:21] offset:288
	s_waitcnt lgkmcnt(0)
	v_pk_mul_f32 v[16:17], v[16:17], v[192:193] op_sel_hi:[1,0]
	v_pk_mul_f32 v[18:19], v[18:19], v[192:193] op_sel_hi:[1,0]
	v_pk_mul_f32 v[12:13], v[12:13], v[192:193] op_sel_hi:[1,0]
	v_pk_mul_f32 v[14:15], v[14:15], v[192:193] op_sel_hi:[1,0]
	v_pk_mul_f32 v[8:9], v[8:9], v[192:193] op_sel_hi:[1,0]
	v_pk_mul_f32 v[10:11], v[10:11], v[192:193] op_sel_hi:[1,0]
	v_pk_mul_f32 v[4:5], v[4:5], v[192:193] op_sel_hi:[1,0]
	v_pk_mul_f32 v[6:7], v[6:7], v[192:193] op_sel_hi:[1,0]
	v_pk_mul_f32 v[16:17], v[224:225], v[16:17]
	v_pk_mul_f32 v[18:19], v[226:227], v[18:19]
	v_pk_mul_f32 v[12:13], v[242:243], v[12:13]
	v_pk_mul_f32 v[14:15], v[244:245], v[14:15]
	v_pk_mul_f32 v[8:9], v[246:247], v[8:9]
	v_pk_mul_f32 v[10:11], v[248:249], v[10:11]
	v_pk_mul_f32 v[4:5], v[136:137], v[4:5]
	v_pk_mul_f32 v[6:7], v[138:139], v[6:7]
	v_cvt_pk_bf16_f32 v16, v16, v17
	v_cvt_pk_bf16_f32 v17, v18, v19
	v_cvt_pk_bf16_f32 v12, v12, v13
	v_cvt_pk_bf16_f32 v13, v14, v15
	v_cvt_pk_bf16_f32 v8, v8, v9
	v_cvt_pk_bf16_f32 v9, v10, v11
	v_cvt_pk_bf16_f32 v4, v4, v5
	v_cvt_pk_bf16_f32 v5, v6, v7
	v_add_u32_e32 v145, 0x58000, v144
	global_store_dwordx2 v145, v[16:17], s[20:21]
	global_store_dwordx2 v145, v[12:13], s[20:21] offset:32
	global_store_dwordx2 v145, v[8:9], s[20:21] offset:256
	global_store_dwordx2 v145, v[4:5], s[20:21] offset:288

	.amdhsa_kernel _Z6mk_fwd4Args
		.amdhsa_group_segment_fixed_size 0
		.amdhsa_private_segment_fixed_size 0
		.amdhsa_kernarg_size 488
		.amdhsa_user_sgpr_count 2
		.amdhsa_user_sgpr_dispatch_ptr 0
		.amdhsa_user_sgpr_queue_ptr 0
		.amdhsa_user_sgpr_kernarg_segment_ptr 1
		.amdhsa_user_sgpr_dispatch_id 0
		.amdhsa_user_sgpr_kernarg_preload_length 0
		.amdhsa_user_sgpr_kernarg_preload_offset 0
		.amdhsa_user_sgpr_private_segment_size 0
		.amdhsa_uses_dynamic_stack 0
		.amdhsa_enable_private_segment 0
		.amdhsa_system_sgpr_workgroup_id_x 1
		.amdhsa_system_sgpr_workgroup_id_y 0
		.amdhsa_system_sgpr_workgroup_id_z 0
		.amdhsa_system_sgpr_workgroup_info 0
		.amdhsa_system_vgpr_workitem_id 0
		.amdhsa_next_free_vgpr 256
		.amdhsa_next_free_sgpr 100
		.amdhsa_accum_offset 256
		.amdhsa_reserve_vcc 1
		.amdhsa_float_round_mode_32 0
		.amdhsa_float_round_mode_16_64 0
		.amdhsa_float_denorm_mode_32 3
		.amdhsa_float_denorm_mode_16_64 3
		.amdhsa_dx10_clamp 1
		.amdhsa_ieee_mode 1
		.amdhsa_fp16_overflow 0
		.amdhsa_tg_split 0
		.amdhsa_exception_fp_ieee_invalid_op 0
		.amdhsa_exception_fp_denorm_src 0
		.amdhsa_exception_fp_ieee_div_zero 0
		.amdhsa_exception_fp_ieee_overflow 0
		.amdhsa_exception_fp_ieee_underflow 0
		.amdhsa_exception_fp_ieee_inexact 0
		.amdhsa_exception_int_div_zero 0
	.end_amdhsa_kernel

.Lfunc_end0:
	.size	_Z6mk_fwd4Args, .Lfunc_end0-_Z6mk_fwd4Args
	.set _Z6mk_fwd4Args.num_vgpr, 256
	.set _Z6mk_fwd4Args.num_agpr, 0
	.set _Z6mk_fwd4Args.numbered_sgpr, 100
	.set _Z6mk_fwd4Args.num_named_barrier, 0
	.set _Z6mk_fwd4Args.private_seg_size, 0
	.set _Z6mk_fwd4Args.uses_vcc, 1
	.set _Z6mk_fwd4Args.uses_flat_scratch, 0
	.set _Z6mk_fwd4Args.has_dyn_sized_stack, 0
	.set _Z6mk_fwd4Args.has_recursion, 0
	.set _Z6mk_fwd4Args.has_indirect_call, 0

amdhsa.kernels:
  - .agpr_count:     0
    .args:
      - .offset:         0
        .size:           232
        .value_kind:     by_value
      - .offset:         232
        .size:           4
        .value_kind:     hidden_block_count_x
      - .offset:         236
        .size:           4
        .value_kind:     hidden_block_count_y
      - .offset:         240
        .size:           4
        .value_kind:     hidden_block_count_z
      - .offset:         244
        .size:           2
        .value_kind:     hidden_group_size_x
      - .offset:         246
        .size:           2
        .value_kind:     hidden_group_size_y
      - .offset:         248
        .size:           2
        .value_kind:     hidden_group_size_z
      - .offset:         250
        .size:           2
        .value_kind:     hidden_remainder_x
      - .offset:         252
        .size:           2
        .value_kind:     hidden_remainder_y
      - .offset:         254
        .size:           2
        .value_kind:     hidden_remainder_z
      - .offset:         272
        .size:           8
        .value_kind:     hidden_global_offset_x
      - .offset:         280
        .size:           8
        .value_kind:     hidden_global_offset_y
      - .offset:         288
        .size:           8
        .value_kind:     hidden_global_offset_z
      - .offset:         296
        .size:           2
        .value_kind:     hidden_grid_dims
      - .offset:         352
        .size:           4
        .value_kind:     hidden_dynamic_lds_size
    .group_segment_fixed_size: 0
    .kernarg_segment_align: 8
    .kernarg_segment_size: 488
    .language:       OpenCL C
    .language_version:
      - 2
      - 0
    .max_flat_workgroup_size: 512
    .name:           _Z6mk_fwd4Args
    .private_segment_fixed_size: 0
    .sgpr_count:     106
    .sgpr_spill_count: 166
    .symbol:         _Z6mk_fwd4Args.kd
    .uniform_work_group_size: 1
    .uses_dynamic_stack: false
    .vgpr_count:     256
    .vgpr_spill_count: 0
    .wavefront_size: 64
